# v31 + SSD state image sb written as paired dwords (DPP swap + v_perm)
# speedup vs baseline: 1.0006x; 1.0006x over previous
.LBB0_258:
	s_or_b64 exec, exec, s[8:9]
	s_and_b32 s8, s64, 31
	s_bfe_u32 s56, s64, 0x20003
	s_lshl_b32 s48, s8, 7
	s_lshl_b32 s57, s56, 8
	v_ashrrev_i32_e32 v42, 7, v0
	s_lshl_b32 s8, s26, 1
	s_waitcnt vmcnt(0)
	v_mul_f32_e32 v29, 0x3fb8aa3b, v30
	v_and_b32_e32 v50, 15, v0
	v_lshlrev_b32_e32 v30, 4, v42
	s_add_u32 s8, s72, s8
	v_bfe_u32 v27, v0, 4, 2
	v_exp_f32_e32 v57, v29
	v_bfe_u32 v29, v0, 6, 1
	v_ashrrev_i32_e32 v31, 31, v30
	s_addc_u32 s9, s73, 0
	v_lshlrev_b32_e32 v34, 1, v50
	v_mov_b32_e32 v35, v1
	v_lshlrev_b32_e32 v48, 6, v29
	v_lshl_add_u64 v[32:33], s[44:45], 0, v[30:31]
	v_lshlrev_b32_e32 v31, 2, v27
	v_lshl_add_u64 v[36:37], s[8:9], 0, v[34:35]
	v_mov_b32_e32 v49, v1
	v_or_b32_e32 v32, v32, v31
	v_lshl_add_u64 v[36:37], v[36:37], 0, v[48:49]
	s_movk_i32 s0, 0x2a00
	v_mad_u64_u32 v[36:37], s[8:9], v32, s0, v[36:37]
	s_movk_i32 s8, 0x2000
	v_mad_i32_i24 v37, v33, s0, v37
	v_add_co_u32_e32 v32, vcc, s8, v36
	s_movk_i32 s1, 0x5000
	s_nop 0
	v_addc_co_u32_e32 v33, vcc, 0, v37, vcc
	v_add_co_u32_e32 v38, vcc, s1, v36
	s_movk_i32 s1, 0x7000
	s_nop 0
	v_addc_co_u32_e32 v39, vcc, 0, v37, vcc
	v_add_co_u32_e32 v40, vcc, s1, v36
	v_and_b32_e32 v52, 63, v0
	s_nop 0
	v_addc_co_u32_e32 v41, vcc, 0, v37, vcc
	global_load_ushort v84, v[36:37], off
	global_load_ushort v86, v[32:33], off offset:2560
	global_load_ushort v164, v[38:39], off offset:1024
	global_load_ushort v163, v[40:41], off offset:3584
	global_load_ushort v160, v[36:37], off offset:32
	global_load_ushort v141, v[40:41], off offset:3616
	global_load_ushort v153, v[38:39], off offset:1056
	global_load_ushort v154, v[32:33], off offset:2592
	v_lshlrev_b32_e32 v32, 2, v52
	v_or_b32_e32 v36, v30, v50
	s_movk_i32 s24, 0x110
	s_movk_i32 s28, 0x90
	v_add_u32_e32 v49, s88, v32
	v_add_u32_e32 v61, s91, v32
	v_add_u32_e32 v67, s79, v32
	v_mov_b32_e32 v33, s89
	v_lshl_add_u32 v32, v3, 1, s89
	v_mul_lo_u32 v37, v36, s24
	v_and_b32_e32 v39, 48, v0
	v_mul_lo_u32 v44, v36, s28
	v_add_u32_e32 v37, s89, v37
	v_lshlrev_b32_e32 v38, 3, v27
	v_add3_u32 v91, s81, v44, v39
	v_bitop3_b32 v44, v30, 56, v50 bitop3:0xc8
	v_lshlrev_b32_e32 v45, 7, v36
	v_mad_u64_u32 v[62:63], s[22:23], v4, s24, v[32:33]
	v_add_u32_e32 v90, v37, v39
	v_sub_u32_e32 v37, v37, v45
	v_bitop3_b32 v36, v36, v38, 56 bitop3:0x6c
	v_bitop3_b32 v44, v38, v44, 32 bitop3:0x36
	s_movk_i32 s22, 0x8e
	v_lshlrev_b32_e32 v35, 2, v28
	v_lshl_add_u32 v92, v36, 1, v37
	v_lshl_add_u32 v93, v44, 1, v37
	v_xor_b32_e32 v37, v5, v4
	v_mul_u32_u24_e32 v44, 0x48, v3
	v_mad_u32_u24 v3, v3, s22, v32
	v_mad_u64_u32 v[64:65], s[22:23], v26, s24, v[32:33]
	v_xor_b32_e32 v32, v26, v5
	v_add_u32_e32 v88, s91, v35
	v_add_u32_e32 v89, s79, v35
	v_xor_b32_e32 v35, v5, v28
	v_lshlrev_b32_e32 v37, 1, v37
	v_lshlrev_b32_e32 v32, 1, v32
	s_movk_i32 s22, 0x48
	v_or_b32_e32 v54, v31, v30
	v_add_u32_e32 v63, v3, v37
	v_add_u32_e32 v65, v3, v32
	v_mad_u32_u24 v3, v5, s22, v35
	v_lshlrev_b32_e32 v44, 1, v44
	v_lshl_add_u32 v96, v3, 1, s89
	v_or_b32_e32 v3, v48, v50
	v_mul_lo_u32 v5, v54, s24
	v_or_b32_e32 v56, 1, v54
	v_add3_u32 v95, s89, v32, v44
	v_add_u32_e32 v5, s65, v5
	v_lshlrev_b32_e32 v32, 1, v3
	v_mul_lo_u32 v35, v56, s24
	v_lshlrev_b32_e32 v43, 5, v29
	v_add3_u32 v94, s89, v37, v44
	v_add_u32_e32 v97, v5, v32
	v_add3_u32 v98, s65, v35, v32
	v_or_b32_e32 v32, 16, v3
	v_or_b32_e32 v35, 32, v3
	v_or_b32_e32 v37, 48, v3
	v_lshl_add_u32 v101, v32, 1, v5
	v_lshl_add_u32 v102, v35, 1, v5
	v_lshl_add_u32 v103, v37, 1, v5
	v_or_b32_e32 v5, v43, v50
	v_mul_u32_u24_e32 v44, 0x88, v5
	v_lshlrev_b32_e32 v31, 1, v29
	v_lshlrev_b32_e32 v44, 1, v44
	v_add_u32_e32 v40, s89, v39
	v_cmp_le_i32_e64 s[22:23], v31, v42
	v_cmp_lt_i32_e64 s[24:25], v31, v42
	v_or_b32_e32 v31, 16, v5
	v_add_u32_e32 v45, 0x1100, v44
	v_add_u32_e32 v41, s65, v39
	v_add_u32_e32 v104, v40, v44
	v_add_u32_e32 v109, v40, v45
	v_mul_u32_u24_e32 v40, 0x48, v31
	v_or_b32_e32 v36, 32, v38
	v_add_u32_e32 v110, v41, v45
	v_lshl_add_u32 v40, v40, 1, s89
	v_bitop3_b32 v45, v31, v38, 56 bitop3:0x6c
	v_lshl_add_u32 v111, v45, 1, v40
	v_bitop3_b32 v45, v31, v36, 56 bitop3:0x6c
	v_lshl_add_u32 v112, v45, 1, v40
	v_bitop3_b32 v45, v31, v54, 56 bitop3:0x6c
	v_or_b32_e32 v60, 2, v54
	v_lshl_add_u32 v113, v45, 1, v40
	v_bitop3_b32 v45, v31, v56, 56 bitop3:0x6c
	v_or_b32_e32 v58, 3, v54
	v_lshl_add_u32 v114, v45, 1, v40
	v_bitop3_b32 v45, v31, v60, 56 bitop3:0x6c
	v_lshl_add_u32 v115, v45, 1, v40
	v_bitop3_b32 v45, v31, v58, 56 bitop3:0x6c
	v_lshl_add_u32 v116, v45, 1, v40
	v_lshl_add_u32 v29, v29, 8, s88
	v_lshlrev_b32_e32 v40, 6, v42
	v_add3_u32 v117, v29, v40, v39
	v_and_b32_e32 v29, 8, v0
	v_mad_u32_u24 v3, v3, s28, v33
	v_bitop3_b32 v39, v38, v0, 8 bitop3:0x78
	v_bitop3_b32 v29, v38, v29, 32 bitop3:0x36
	v_lshl_add_u32 v118, v39, 1, v3
	v_lshl_add_u32 v119, v29, 1, v3
	v_mad_u32_u24 v3, v32, s28, v33
	v_bitop3_b32 v29, v32, v38, 24 bitop3:0x6c
	v_lshl_add_u32 v120, v29, 1, v3
	v_bitop3_b32 v29, v32, v36, 24 bitop3:0x6c
	v_lshl_add_u32 v121, v29, 1, v3
	v_mad_u32_u24 v3, v35, s28, v33
	v_bitop3_b32 v29, v35, v38, 40 bitop3:0x6c
	v_lshl_add_u32 v122, v29, 1, v3
	v_bitop3_b32 v29, v35, v36, 40 bitop3:0x6c
	v_lshl_add_u32 v123, v29, 1, v3
	v_mad_u32_u24 v3, v37, s28, v33
	v_bitop3_b32 v29, v37, v38, 56 bitop3:0x6c
	v_lshl_add_u32 v124, v29, 1, v3
	v_bitop3_b32 v29, v37, v36, 56 bitop3:0x6c
	v_lshl_add_u32 v125, v29, 1, v3
	v_lshlrev_b32_e32 v3, 2, v5
	v_add_u32_e32 v126, s91, v3
	v_add_u32_e32 v127, s79, v3
	v_mul_lo_u32 v3, v54, s28
	v_lshlrev_b32_e32 v29, 1, v5
	v_add3_u32 v128, s81, v3, v29
	v_lshlrev_b32_e32 v3, 2, v31
	v_add_u32_e32 v132, s91, v3
	v_add_u32_e32 v133, s79, v3
	v_mul_u32_u24_e32 v3, 0x48, v5
	v_lshl_add_u32 v3, v3, 1, s89
	v_bitop3_b32 v32, v5, v38, 40 bitop3:0x6c
	v_or_b32_e32 v66, s26, v31
	v_cmp_gt_i32_e64 s[26:27], v5, v54
	v_cmp_gt_i32_e64 s[28:29], v5, v56
	v_cmp_gt_i32_e64 s[30:31], v5, v60
	v_cmp_gt_i32_e64 s[34:35], v5, v58
	v_cmp_gt_i32_e64 s[36:37], v31, v54
	v_cmp_gt_i32_e64 s[38:39], v31, v56
	v_cmp_gt_i32_e64 s[40:41], v31, v60
	v_cmp_gt_i32_e64 s[42:43], v31, v58
	v_bitop3_b32 v31, v43, 40, v50 bitop3:0xc8
	v_lshl_add_u32 v135, v32, 1, v3
	v_bitop3_b32 v32, v5, v36, 40 bitop3:0x6c
	v_bitop3_b32 v5, v5, v54, 40 bitop3:0x6c
	v_lshl_add_u32 v137, v5, 1, v3
	v_bitop3_b32 v5, v54, v31, 1 bitop3:0x36
	s_lshl_b64 s[84:85], s[2:3], 18
	v_lshl_add_u32 v138, v5, 1, v3
	v_bitop3_b32 v5, v54, v31, 2 bitop3:0x36
	s_add_u32 s84, s84, 0x2e793000
	v_lshl_add_u32 v136, v32, 1, v3
	v_lshl_add_u32 v139, v5, 1, v3
	v_bitop3_b32 v5, v54, v31, 3 bitop3:0x36
	s_addc_u32 s85, s85, 0
	v_lshlrev_b64 v[32:33], 7, v[0:1]
	v_lshl_add_u32 v140, v5, 1, v3
	v_lshl_add_u64 v[68:69], s[84:85], 0, v[32:33]
	s_mul_hi_i32 s84, s2, 0x1500000
	s_mul_i32 s85, s2, 0x1500000
	v_mul_hi_u32_u24_e32 v3, 0xa800, v27
	v_mul_u32_u24_e32 v5, 0xa800, v27
	v_or_b32_e32 v33, s84, v3
	v_or_b32_e32 v32, s85, v5
	v_mad_i64_i32 v[30:31], s[84:85], v30, s0, v[32:33]
	v_ashrrev_i32_e32 v55, 31, v54
	v_lshl_add_u64 v[70:71], v[30:31], 0, s[48:49]
	s_lshl_b64 s[84:85], s[2:3], 23
	v_lshlrev_b64 v[30:31], 12, v[54:55]
	v_lshl_add_u64 v[72:73], s[84:85], 0, v[30:31]
	s_mul_i32 s84, s2, 0xc00000
	v_or3_b32 v72, s48, v29, v72
	s_or_b32 s48, s84, s48
	s_mul_hi_i32 s85, s2, 0xc00000
	s_add_u32 s84, s48, 0x1f9f1000
	s_addc_u32 s85, s85, 0
	v_and_b32_e32 v3, 64, v0
	v_mov_b64_e32 v[30:31], s[84:85]
	s_mul_i32 s56, s56, 0x22000
	v_lshl_add_u32 v59, v0, 2, s88
	v_or3_b32 v70, v70, v3, v34
	v_mad_i64_i32 v[74:75], s[84:85], v28, s82, v[30:31]
	v_and_b32_e32 v0, 7, v0
	v_mad_i64_i32 v[26:27], s[84:85], v26, s82, 0
	v_mov_b32_e32 v3, 0xc00000
	v_mad_i64_i32 v[4:5], s[84:85], v4, s82, 0
	v_lshl_or_b32 v74, v0, 4, v74
	v_mad_i64_i32 v[76:77], s[84:85], s2, v3, v[26:27]
	v_lshlrev_b32_e32 v0, 4, v50
	v_mad_i64_i32 v[78:79], s[84:85], s2, v3, v[4:5]
	s_add_u32 s48, s93, s56
	v_or3_b32 v76, v76, s57, v0
	v_or3_b32 v78, v78, s57, v0
	s_addc_u32 s84, s4, 0
	s_lshl_b64 s[56:57], s[2:3], 14
	s_add_u32 s56, s48, s56
	s_addc_u32 s57, s84, s57
	v_lshlrev_b32_e32 v0, 3, v52
	v_lshl_add_u64 v[80:81], s[56:57], 0, v[0:1]
	s_lshl_b64 s[56:57], s[2:3], 22
	v_lshlrev_b64 v[4:5], 11, v[54:55]
	v_cmp_eq_u32_e64 s[8:9], 0, v50
	v_cmp_eq_u32_e64 s[10:11], 0, v52
	v_cmp_gt_u32_e64 s[12:13], 2, v52
	v_cmp_gt_u32_e64 s[14:15], 4, v52
	v_cmp_gt_u32_e64 s[16:17], 8, v52
	v_cmp_gt_u32_e64 s[18:19], 16, v52
	v_cmp_gt_u32_e64 s[20:21], 32, v52
	v_add_u32_e32 v99, 0x110, v98
	v_add_u32_e32 v100, 0x220, v98
	v_lshl_add_u32 v105, v54, 2, s91
	v_lshl_add_u32 v106, v56, 2, s91
	v_lshl_add_u32 v107, v60, 2, s91
	v_lshl_add_u32 v108, v58, 2, s91
	v_add_u32_e32 v129, 0x90, v128
	v_add_u32_e32 v130, 0x120, v128
	v_add_u32_e32 v131, 0x1b0, v128
	v_add_u32_e32 v134, v41, v44
	v_lshl_or_b32 v68, v46, 2, v68
	v_lshl_add_u64 v[82:83], s[56:57], 0, v[4:5]
	s_mov_b64 s[56:57], 0
	v_mov_b32_e32 v3, v2
	v_mov_b32_e32 v4, v2
	v_mov_b32_e32 v5, v2
	v_mov_b32_e32 v34, v2
	v_mov_b32_e32 v35, v2
	v_mov_b32_e32 v36, v2
	v_mov_b32_e32 v37, v2
	v_mov_b32_e32 v30, v2
	v_mov_b32_e32 v31, v2
	v_mov_b32_e32 v32, v2
	v_mov_b32_e32 v33, v2
	v_mov_b32_e32 v26, v2
	v_mov_b32_e32 v27, v2
	v_mov_b32_e32 v28, v2
	v_mov_b32_e32 v29, v2
	v_and_b32_e32 v210, 1, v177
	v_cmp_eq_u32_e64 s[98:99], 1, v210
	v_mov_b32_e32 v211, 0x10e
	v_mov_b32_e32 v212, 0x5040100
	v_mov_b32_e32 v213, 0x3020706
	v_cndmask_b32_e64 v211, 0, v211, s[98:99]
	v_cndmask_b32_e64 v209, v212, v213, s[98:99]
	v_add_u32_e32 v208, v97, v211
	s_branch .LBB0_260

.LBB0_264:
	s_or_b64 exec, exec, s[84:85]
	s_waitcnt lgkmcnt(0)
	s_barrier
	s_waitcnt vmcnt(11)
	ds_write_b128 v62, v[10:13]
	ds_write_b128 v62, v[6:9] offset:17408
	ds_write_b16 v63, v6 offset:34816
	ds_write_b16_d16_hi v94, v6 offset:34960
	ds_write_b16 v63, v7 offset:35104
	ds_write_b16_d16_hi v63, v7 offset:35248
	ds_write_b16 v63, v8 offset:35392
	ds_write_b16_d16_hi v63, v8 offset:35536
	ds_write_b16 v63, v9 offset:35680
	ds_write_b16_d16_hi v63, v9 offset:35824
	s_waitcnt vmcnt(9)
	ds_write_b128 v64, v[18:21]
	ds_write_b128 v64, v[14:17] offset:17408
	ds_write_b16 v65, v14 offset:34816
	ds_write_b16_d16_hi v95, v14 offset:34960
	ds_write_b16 v65, v15 offset:35104
	ds_write_b16_d16_hi v65, v15 offset:35248
	ds_write_b16 v65, v16 offset:35392
	ds_write_b16_d16_hi v65, v16 offset:35536
	ds_write_b16 v65, v17 offset:35680
	ds_write_b16_d16_hi v65, v17 offset:35824
	v_mov_b32_e32 v0, s92
	ds_read_b32 v0, v0
	ds_read_b32 v38, v88
	s_cmp_eq_u32 s56, 0x3e0000
	s_waitcnt lgkmcnt(0)
	v_sub_f32_e32 v0, v0, v38
	v_mul_f32_e32 v0, 0x3fb8aa3b, v0
	ds_read_b32 v38, v89
	v_exp_f32_e32 v0, v0
	s_waitcnt vmcnt(8)
	ds_write_b16 v96, v22 offset:53248
	ds_write_b16_d16_hi v96, v22 offset:53392
	s_waitcnt lgkmcnt(2)
	v_mul_f32_e32 v0, v38, v0
	v_lshlrev_b32_e32 v38, 16, v22
	v_mul_f32_e32 v38, v0, v38
	v_cvt_pk_bf16_f32 v38, v38, v38
	ds_write_b16 v96, v38 offset:62464
	v_and_b32_e32 v38, 0xffff0000, v22
	v_mul_f32_e32 v38, v0, v38
	v_cvt_pk_bf16_f32 v38, v38, v38
	ds_write_b16 v96, v38 offset:62608
	ds_write_b16 v96, v23 offset:53536
	ds_write_b16_d16_hi v96, v23 offset:53680
	v_lshlrev_b32_e32 v38, 16, v23
	v_mul_f32_e32 v38, v0, v38
	v_cvt_pk_bf16_f32 v38, v38, v38
	ds_write_b16 v96, v38 offset:62752
	v_and_b32_e32 v38, 0xffff0000, v23
	v_mul_f32_e32 v38, v0, v38
	v_cvt_pk_bf16_f32 v38, v38, v38
	ds_write_b16 v96, v38 offset:62896
	ds_write_b16 v96, v24 offset:53824
	ds_write_b16_d16_hi v96, v24 offset:53968
	v_lshlrev_b32_e32 v38, 16, v24
	v_mul_f32_e32 v38, v0, v38
	v_cvt_pk_bf16_f32 v38, v38, v38
	ds_write_b16 v96, v38 offset:63040
	v_and_b32_e32 v38, 0xffff0000, v24
	v_mul_f32_e32 v38, v0, v38
	v_cvt_pk_bf16_f32 v38, v38, v38
	ds_write_b16 v96, v38 offset:63184
	ds_write_b16 v96, v25 offset:54112
	ds_write_b16_d16_hi v96, v25 offset:54256
	v_lshlrev_b32_e32 v38, 16, v25
	v_mul_f32_e32 v38, v0, v38
	v_cvt_pk_bf16_f32 v38, v38, v38
	ds_write_b16 v96, v38 offset:63328
	v_and_b32_e32 v38, 0xffff0000, v25
	v_mul_f32_e32 v0, v0, v38
	v_cvt_pk_bf16_f32 v0, v0, v0
	ds_write_b16 v96, v0 offset:63472
	v_cvt_pk_bf16_f32 v210, v2, v3
	v_cvt_pk_bf16_f32 v212, v4, v5
	v_cvt_pk_bf16_f32 v214, v34, v35
	v_mov_b32_dpp v211, v210 quad_perm:[1,0,3,2] row_mask:0xf bank_mask:0xf
	v_perm_b32 v211, v211, v210, v209
	ds_write_b32 v208, v211
	v_cvt_pk_bf16_f32 v210, v36, v37
	v_mov_b32_dpp v213, v212 quad_perm:[1,0,3,2] row_mask:0xf bank_mask:0xf
	v_perm_b32 v213, v213, v212, v209
	ds_write_b32 v208, v213 offset:544
	v_cvt_pk_bf16_f32 v212, v30, v31
	v_mov_b32_dpp v215, v214 quad_perm:[1,0,3,2] row_mask:0xf bank_mask:0xf
	v_perm_b32 v215, v215, v214, v209
	ds_write_b32 v208, v215 offset:32
	v_cvt_pk_bf16_f32 v214, v32, v33
	v_mov_b32_dpp v211, v210 quad_perm:[1,0,3,2] row_mask:0xf bank_mask:0xf
	v_perm_b32 v211, v211, v210, v209
	ds_write_b32 v208, v211 offset:576
	v_cvt_pk_bf16_f32 v210, v26, v27
	v_mov_b32_dpp v213, v212 quad_perm:[1,0,3,2] row_mask:0xf bank_mask:0xf
	v_perm_b32 v213, v213, v212, v209
	ds_write_b32 v208, v213 offset:64
	v_cvt_pk_bf16_f32 v212, v28, v29
	v_mov_b32_dpp v215, v214 quad_perm:[1,0,3,2] row_mask:0xf bank_mask:0xf
	v_perm_b32 v215, v215, v214, v209
	ds_write_b32 v208, v215 offset:608
	s_nop 0
	v_mov_b32_dpp v211, v210 quad_perm:[1,0,3,2] row_mask:0xf bank_mask:0xf
	v_perm_b32 v211, v211, v210, v209
	ds_write_b32 v208, v211 offset:96
	s_nop 0
	v_mov_b32_dpp v213, v212 quad_perm:[1,0,3,2] row_mask:0xf bank_mask:0xf
	v_perm_b32 v213, v213, v212, v209
	ds_write_b32 v208, v213 offset:640
	s_cbranch_scc1 .LBB0_268
	v_lshl_add_u64 v[6:7], s[50:51], 0, v[78:79]
	v_add_co_u32_e32 v10, vcc, 0x1f9f2000, v6
	v_lshl_add_u64 v[14:15], s[50:51], 0, v[76:77]
	s_nop 0
	v_addc_co_u32_e32 v11, vcc, 0, v7, vcc
	v_add_co_u32_e32 v18, vcc, 0x1f9f2000, v14
	v_lshl_add_u64 v[22:23], s[50:51], 0, v[74:75]
	s_nop 0
	v_addc_co_u32_e32 v19, vcc, 0, v15, vcc
	global_load_dwordx4 v[6:9], v[10:11], off
	s_nop 0
	global_load_dwordx4 v[10:13], v[10:11], off offset:1024
	s_nop 0
	global_load_dwordx4 v[14:17], v[18:19], off
	s_nop 0
	global_load_dwordx4 v[18:21], v[18:19], off offset:1024
	s_nop 0
	global_load_dwordx4 v[22:25], v[22:23], off
	s_and_saveexec_b64 s[84:85], s[6:7]
	s_cbranch_execz .LBB0_267
	v_lshl_add_u64 v[38:39], s[50:51], 0, v[68:69]
	global_load_dword v53, v[38:39], off
